# GEMM K-loops: MFMA-phase priority dropped two MFMA groups (8 MFMAs) before the phase ends
# speedup vs baseline: 1.0399x; 1.0073x over previous
.LBB0_677:
	s_add_i32 s10, s10, 64
	s_waitcnt lgkmcnt(2)
	v_mfma_f32_16x16x32_bf16 v[162:165], v[202:205], v[178:181], v[162:165]
	v_mfma_f32_16x16x32_bf16 v[154:157], v[202:205], v[182:185], v[154:157]
	v_mfma_f32_16x16x32_bf16 v[134:137], v[202:205], v[186:189], v[134:137]
	v_mfma_f32_16x16x32_bf16 v[114:117], v[202:205], v[190:193], v[114:117]
	ds_read_b128 v[202:205], v216 offset:8192
	s_waitcnt lgkmcnt(2)
	v_mfma_f32_16x16x32_bf16 v[82:85], v[198:201], v[190:193], v[82:85]
	v_mfma_f32_16x16x32_bf16 v[86:89], v[198:201], v[186:189], v[86:89]
	v_mfma_f32_16x16x32_bf16 v[90:93], v[198:201], v[182:185], v[90:93]
	v_mfma_f32_16x16x32_bf16 v[94:97], v[198:201], v[178:181], v[94:97]
	ds_read_b128 v[198:201], v216 offset:10240
	s_waitcnt lgkmcnt(2)
	v_mfma_f32_16x16x32_bf16 v[78:81], v[194:197], v[178:181], v[78:81]
	v_mfma_f32_16x16x32_bf16 v[74:77], v[194:197], v[182:185], v[74:77]
	v_mfma_f32_16x16x32_bf16 v[70:73], v[194:197], v[186:189], v[70:73]
	v_mfma_f32_16x16x32_bf16 v[66:69], v[194:197], v[190:193], v[66:69]
	ds_read_b128 v[194:197], v216 offset:12288
	s_waitcnt lgkmcnt(2)
	v_mfma_f32_16x16x32_bf16 v[50:53], v[202:205], v[190:193], v[50:53]
	v_mfma_f32_16x16x32_bf16 v[54:57], v[202:205], v[186:189], v[54:57]
	v_mfma_f32_16x16x32_bf16 v[58:61], v[202:205], v[182:185], v[58:61]
	v_mfma_f32_16x16x32_bf16 v[62:65], v[202:205], v[178:181], v[62:65]
	ds_read_b128 v[202:205], v216 offset:14336
	s_waitcnt lgkmcnt(2)
	v_mfma_f32_16x16x32_bf16 v[46:49], v[198:201], v[178:181], v[46:49]
	v_mfma_f32_16x16x32_bf16 v[42:45], v[198:201], v[182:185], v[42:45]
	v_mfma_f32_16x16x32_bf16 v[38:41], v[198:201], v[186:189], v[38:41]
	v_mfma_f32_16x16x32_bf16 v[34:37], v[198:201], v[190:193], v[34:37]
	s_setprio 0
	s_waitcnt lgkmcnt(1)
	v_mfma_f32_16x16x32_bf16 v[6:9], v[194:197], v[190:193], v[6:9]
	v_mfma_f32_16x16x32_bf16 v[18:21], v[194:197], v[186:189], v[18:21]
	v_mfma_f32_16x16x32_bf16 v[26:29], v[194:197], v[182:185], v[26:29]
	v_mfma_f32_16x16x32_bf16 v[30:33], v[194:197], v[178:181], v[30:33]
	s_waitcnt lgkmcnt(0)
	v_mfma_f32_16x16x32_bf16 v[22:25], v[202:205], v[178:181], v[22:25]
	v_mfma_f32_16x16x32_bf16 v[14:17], v[202:205], v[182:185], v[14:17]
	v_mfma_f32_16x16x32_bf16 v[10:13], v[202:205], v[186:189], v[10:13]
	v_mfma_f32_16x16x32_bf16 v[2:5], v[202:205], v[190:193], v[2:5]
	s_add_u32 s38, s38, 0x80
	s_addc_u32 s39, s39, 0
	s_add_u32 s40, s40, 0x80
	s_addc_u32 s41, s41, 0
	s_and_b64 vcc, exec, s[52:53]
	s_cbranch_vccnz .LBB0_684

.LBB0_1483:
	s_add_i32 s1, s1, 64
	s_waitcnt lgkmcnt(2)
	v_mfma_f32_16x16x32_bf16 v[162:165], v[202:205], v[178:181], v[162:165]
	v_mfma_f32_16x16x32_bf16 v[154:157], v[202:205], v[182:185], v[154:157]
	v_mfma_f32_16x16x32_bf16 v[122:125], v[202:205], v[186:189], v[122:125]
	v_mfma_f32_16x16x32_bf16 v[106:109], v[202:205], v[190:193], v[106:109]
	ds_read_b128 v[202:205], v216 offset:8192
	s_waitcnt lgkmcnt(2)
	v_mfma_f32_16x16x32_bf16 v[82:85], v[198:201], v[190:193], v[82:85]
	v_mfma_f32_16x16x32_bf16 v[86:89], v[198:201], v[186:189], v[86:89]
	v_mfma_f32_16x16x32_bf16 v[90:93], v[198:201], v[182:185], v[90:93]
	v_mfma_f32_16x16x32_bf16 v[94:97], v[198:201], v[178:181], v[94:97]
	ds_read_b128 v[198:201], v216 offset:10240
	s_waitcnt lgkmcnt(2)
	v_mfma_f32_16x16x32_bf16 v[78:81], v[194:197], v[178:181], v[78:81]
	v_mfma_f32_16x16x32_bf16 v[74:77], v[194:197], v[182:185], v[74:77]
	v_mfma_f32_16x16x32_bf16 v[70:73], v[194:197], v[186:189], v[70:73]
	v_mfma_f32_16x16x32_bf16 v[66:69], v[194:197], v[190:193], v[66:69]
	ds_read_b128 v[194:197], v216 offset:12288
	s_waitcnt lgkmcnt(2)
	v_mfma_f32_16x16x32_bf16 v[50:53], v[202:205], v[190:193], v[50:53]
	v_mfma_f32_16x16x32_bf16 v[54:57], v[202:205], v[186:189], v[54:57]
	v_mfma_f32_16x16x32_bf16 v[58:61], v[202:205], v[182:185], v[58:61]
	v_mfma_f32_16x16x32_bf16 v[62:65], v[202:205], v[178:181], v[62:65]
	ds_read_b128 v[202:205], v216 offset:14336
	s_waitcnt lgkmcnt(2)
	v_mfma_f32_16x16x32_bf16 v[46:49], v[198:201], v[178:181], v[46:49]
	v_mfma_f32_16x16x32_bf16 v[42:45], v[198:201], v[182:185], v[42:45]
	v_mfma_f32_16x16x32_bf16 v[38:41], v[198:201], v[186:189], v[38:41]
	v_mfma_f32_16x16x32_bf16 v[34:37], v[198:201], v[190:193], v[34:37]
	s_setprio 0
	s_waitcnt lgkmcnt(1)
	v_mfma_f32_16x16x32_bf16 v[6:9], v[194:197], v[190:193], v[6:9]
	v_mfma_f32_16x16x32_bf16 v[18:21], v[194:197], v[186:189], v[18:21]
	v_mfma_f32_16x16x32_bf16 v[26:29], v[194:197], v[182:185], v[26:29]
	v_mfma_f32_16x16x32_bf16 v[30:33], v[194:197], v[178:181], v[30:33]
	s_waitcnt lgkmcnt(0)
	v_mfma_f32_16x16x32_bf16 v[22:25], v[202:205], v[178:181], v[22:25]
	v_mfma_f32_16x16x32_bf16 v[14:17], v[202:205], v[182:185], v[14:17]
	v_mfma_f32_16x16x32_bf16 v[10:13], v[202:205], v[186:189], v[10:13]
	v_mfma_f32_16x16x32_bf16 v[2:5], v[202:205], v[190:193], v[2:5]
	s_add_u32 s38, s38, 0x80
	s_addc_u32 s39, s39, 0
	s_add_u32 s40, s40, 0x80
	s_addc_u32 s41, s41, 0
	s_and_b64 vcc, exec, s[44:45]
	s_cbranch_vccnz .LBB0_1490

.LBB0_1681:
	s_waitcnt lgkmcnt(2)
	v_mfma_f32_16x16x32_bf16 v[162:165], v[202:205], v[178:181], v[162:165]
	v_mfma_f32_16x16x32_bf16 v[166:169], v[202:205], v[182:185], v[166:169]
	v_mfma_f32_16x16x32_bf16 v[170:173], v[202:205], v[186:189], v[170:173]
	v_mfma_f32_16x16x32_bf16 v[174:177], v[202:205], v[190:193], v[174:177]
	ds_read_b128 v[202:205], v217 offset:8192
	s_waitcnt lgkmcnt(2)
	v_mfma_f32_16x16x32_bf16 v[158:161], v[198:201], v[190:193], v[158:161]
	v_mfma_f32_16x16x32_bf16 v[154:157], v[198:201], v[186:189], v[154:157]
	v_mfma_f32_16x16x32_bf16 v[150:153], v[198:201], v[182:185], v[150:153]
	v_mfma_f32_16x16x32_bf16 v[146:149], v[198:201], v[178:181], v[146:149]
	ds_read_b128 v[198:201], v217 offset:10240
	s_waitcnt lgkmcnt(2)
	v_mfma_f32_16x16x32_bf16 v[118:121], v[194:197], v[178:181], v[118:121]
	v_mfma_f32_16x16x32_bf16 v[122:125], v[194:197], v[182:185], v[122:125]
	v_mfma_f32_16x16x32_bf16 v[126:129], v[194:197], v[186:189], v[126:129]
	v_mfma_f32_16x16x32_bf16 v[130:133], v[194:197], v[190:193], v[130:133]
	ds_read_b128 v[194:197], v217 offset:12288
	s_waitcnt lgkmcnt(2)
	v_mfma_f32_16x16x32_bf16 v[110:113], v[202:205], v[190:193], v[110:113]
	v_mfma_f32_16x16x32_bf16 v[106:109], v[202:205], v[186:189], v[106:109]
	v_mfma_f32_16x16x32_bf16 v[102:105], v[202:205], v[182:185], v[102:105]
	v_mfma_f32_16x16x32_bf16 v[98:101], v[202:205], v[178:181], v[98:101]
	ds_read_b128 v[202:205], v217 offset:14336
	s_waitcnt lgkmcnt(2)
	v_mfma_f32_16x16x32_bf16 v[82:85], v[198:201], v[178:181], v[82:85]
	v_mfma_f32_16x16x32_bf16 v[86:89], v[198:201], v[182:185], v[86:89]
	v_mfma_f32_16x16x32_bf16 v[90:93], v[198:201], v[186:189], v[90:93]
	v_mfma_f32_16x16x32_bf16 v[94:97], v[198:201], v[190:193], v[94:97]
	s_setprio 0
	s_waitcnt lgkmcnt(1)
	v_mfma_f32_16x16x32_bf16 v[78:81], v[194:197], v[190:193], v[78:81]
	v_mfma_f32_16x16x32_bf16 v[74:77], v[194:197], v[186:189], v[74:77]
	v_mfma_f32_16x16x32_bf16 v[70:73], v[194:197], v[182:185], v[70:73]
	v_mfma_f32_16x16x32_bf16 v[66:69], v[194:197], v[178:181], v[66:69]
	s_waitcnt lgkmcnt(0)
	v_mfma_f32_16x16x32_bf16 v[50:53], v[202:205], v[178:181], v[50:53]
	v_mfma_f32_16x16x32_bf16 v[54:57], v[202:205], v[182:185], v[54:57]
	v_mfma_f32_16x16x32_bf16 v[58:61], v[202:205], v[186:189], v[58:61]
	v_mfma_f32_16x16x32_bf16 v[62:65], v[202:205], v[190:193], v[62:65]
	s_add_u32 s36, s36, 0x80
	s_addc_u32 s37, s37, 0
	s_add_u32 s38, s38, 0x80
	s_addc_u32 s39, s39, 0
	s_cmpk_gt_u32 s1, 0x3bf
	s_cbranch_scc1 .LBB0_1686

.LBB0_1814:
	s_add_i32 s20, s20, 64
	s_waitcnt lgkmcnt(2)
	v_mfma_f32_16x16x32_bf16 v[162:165], v[202:205], v[178:181], v[162:165]
	v_mfma_f32_16x16x32_bf16 v[154:157], v[202:205], v[182:185], v[154:157]
	v_mfma_f32_16x16x32_bf16 v[118:121], v[202:205], v[186:189], v[118:121]
	v_mfma_f32_16x16x32_bf16 v[106:109], v[202:205], v[190:193], v[106:109]
	ds_read_b128 v[202:205], v216 offset:8192
	s_waitcnt lgkmcnt(2)
	v_mfma_f32_16x16x32_bf16 v[82:85], v[198:201], v[190:193], v[82:85]
	v_mfma_f32_16x16x32_bf16 v[86:89], v[198:201], v[186:189], v[86:89]
	v_mfma_f32_16x16x32_bf16 v[90:93], v[198:201], v[182:185], v[90:93]
	v_mfma_f32_16x16x32_bf16 v[94:97], v[198:201], v[178:181], v[94:97]
	ds_read_b128 v[198:201], v216 offset:10240
	s_waitcnt lgkmcnt(2)
	v_mfma_f32_16x16x32_bf16 v[78:81], v[194:197], v[178:181], v[78:81]
	v_mfma_f32_16x16x32_bf16 v[74:77], v[194:197], v[182:185], v[74:77]
	v_mfma_f32_16x16x32_bf16 v[70:73], v[194:197], v[186:189], v[70:73]
	v_mfma_f32_16x16x32_bf16 v[66:69], v[194:197], v[190:193], v[66:69]
	ds_read_b128 v[194:197], v216 offset:12288
	s_waitcnt lgkmcnt(2)
	v_mfma_f32_16x16x32_bf16 v[50:53], v[202:205], v[190:193], v[50:53]
	v_mfma_f32_16x16x32_bf16 v[54:57], v[202:205], v[186:189], v[54:57]
	v_mfma_f32_16x16x32_bf16 v[58:61], v[202:205], v[182:185], v[58:61]
	v_mfma_f32_16x16x32_bf16 v[62:65], v[202:205], v[178:181], v[62:65]
	ds_read_b128 v[202:205], v216 offset:14336
	s_waitcnt lgkmcnt(2)
	v_mfma_f32_16x16x32_bf16 v[46:49], v[198:201], v[178:181], v[46:49]
	v_mfma_f32_16x16x32_bf16 v[42:45], v[198:201], v[182:185], v[42:45]
	v_mfma_f32_16x16x32_bf16 v[38:41], v[198:201], v[186:189], v[38:41]
	v_mfma_f32_16x16x32_bf16 v[34:37], v[198:201], v[190:193], v[34:37]
	s_setprio 0
	s_waitcnt lgkmcnt(1)
	v_mfma_f32_16x16x32_bf16 v[6:9], v[194:197], v[190:193], v[6:9]
	v_mfma_f32_16x16x32_bf16 v[18:21], v[194:197], v[186:189], v[18:21]
	v_mfma_f32_16x16x32_bf16 v[26:29], v[194:197], v[182:185], v[26:29]
	v_mfma_f32_16x16x32_bf16 v[30:33], v[194:197], v[178:181], v[30:33]
	s_waitcnt lgkmcnt(0)
	v_mfma_f32_16x16x32_bf16 v[22:25], v[202:205], v[178:181], v[22:25]
	v_mfma_f32_16x16x32_bf16 v[14:17], v[202:205], v[182:185], v[14:17]
	v_mfma_f32_16x16x32_bf16 v[10:13], v[202:205], v[186:189], v[10:13]
	v_mfma_f32_16x16x32_bf16 v[2:5], v[202:205], v[190:193], v[2:5]
	s_add_u32 s36, s36, 0x80
	s_addc_u32 s37, s37, 0
	s_add_u32 s38, s38, 0x80
	s_addc_u32 s39, s39, 0
	s_and_b64 vcc, exec, s[40:41]
	s_cbranch_vccnz .LBB0_1821
